# EXPERIMENT warm-up read of the pool_in weights before its GEMM (on hand-written P0 + S2)
# baseline (speedup 1.0000x reference)
; #define LAS __attribute__((address_space(3)))
; template <class Epi, class Sched, bool ALIGN_EPI = false, bool SP2 = false>
; __device__ __forceinline__ void gemm_phase(PG8_LAS unsigned char* lds, const Gemm g, const Sched& S, const Epi& E) {
;     ...
;     Unit cur, nxt; int ui = 0;
;     if (!S.next(0, cur)) return;
; __global__ void __launch_bounds__(NWAVES * 64, 2) mk_fwd(Args args) {
;     ...
;             if (IN(8)) {
;                 pg8::Gemm g{WSP(const bf16, WS_HB), WSP(const bf16, WS_W_POOL_IN), M, 16384, D, D, D, 0}; pg8::StaticOrder S; S.init(M, 16384, F.G, (int)blockIdx.x);
;                 pg8::EpiRowScale E{WSP(bf16, WS_ACT_A), 16384, ROWSS(1), (LAS float*)(F.lds + 132096)};
;                 pg8::gemm_phase<pg8::EpiRowScale, pg8::StaticOrder, true, true>(F.lds + RING_OFF, g, S, E);
.LBB0_721:
	s_load_dwordx2 s[2:3], s[74:75], 0x100
	s_waitcnt lgkmcnt(0)
	s_cmp_lt_i32 s2, 9
	s_cselect_b64 s[2:3], -1, 0
	s_and_b64 s[4:5], s[2:3], s[0:1]
	s_andn2_b64 vcc, exec, s[4:5]
	s_cbranch_vccnz .LBB0_752
	s_cmpk_gt_i32 s93, 0x7ff
	v_readfirstlane_b32 s14, v0
	s_cbranch_scc1 .LBB0_752
	s_lshl_b32 s0, s93, 3
	s_lshr_b32 s1, s14, 6
	s_add_i32 s0, s0, s1
	s_lshl_b32 s0, s0, 16
	s_add_u32 s0, s0, 0xd200000
	s_add_u32 s2, s78, s0
	s_addc_u32 s3, s79, 0
	v_lshlrev_b32_e32 v1, 4, v186
	global_load_dwordx4 v[2:5], v1, s[2:3]
	global_load_dwordx4 v[6:9], v1, s[2:3] offset:1024
	global_load_dwordx4 v[10:13], v1, s[2:3] offset:2048
	global_load_dwordx4 v[14:17], v1, s[2:3] offset:3072
	s_add_u32 s2, s2, 0x1000
	s_addc_u32 s3, s3, 0
	global_load_dwordx4 v[18:21], v1, s[2:3]
	global_load_dwordx4 v[22:25], v1, s[2:3] offset:1024
	global_load_dwordx4 v[26:29], v1, s[2:3] offset:2048
	global_load_dwordx4 v[30:33], v1, s[2:3] offset:3072
	s_add_u32 s2, s2, 0x1000
	s_addc_u32 s3, s3, 0
	global_load_dwordx4 v[34:37], v1, s[2:3]
	global_load_dwordx4 v[38:41], v1, s[2:3] offset:1024
	global_load_dwordx4 v[42:45], v1, s[2:3] offset:2048
	global_load_dwordx4 v[46:49], v1, s[2:3] offset:3072
	s_add_u32 s2, s2, 0x1000
	s_addc_u32 s3, s3, 0
	global_load_dwordx4 v[50:53], v1, s[2:3]
	global_load_dwordx4 v[54:57], v1, s[2:3] offset:1024
	global_load_dwordx4 v[58:61], v1, s[2:3] offset:2048
	global_load_dwordx4 v[62:65], v1, s[2:3] offset:3072
	s_waitcnt vmcnt(8)
	s_add_u32 s2, s2, 0x1000
	s_addc_u32 s3, s3, 0
	global_load_dwordx4 v[2:5], v1, s[2:3]
	global_load_dwordx4 v[6:9], v1, s[2:3] offset:1024
	global_load_dwordx4 v[10:13], v1, s[2:3] offset:2048
	global_load_dwordx4 v[14:17], v1, s[2:3] offset:3072
	s_add_u32 s2, s2, 0x1000
	s_addc_u32 s3, s3, 0
	global_load_dwordx4 v[18:21], v1, s[2:3]
	global_load_dwordx4 v[22:25], v1, s[2:3] offset:1024
	global_load_dwordx4 v[26:29], v1, s[2:3] offset:2048
	global_load_dwordx4 v[30:33], v1, s[2:3] offset:3072
	s_add_u32 s2, s2, 0x1000
	s_addc_u32 s3, s3, 0
	global_load_dwordx4 v[34:37], v1, s[2:3]
	global_load_dwordx4 v[38:41], v1, s[2:3] offset:1024
	global_load_dwordx4 v[42:45], v1, s[2:3] offset:2048
	global_load_dwordx4 v[46:49], v1, s[2:3] offset:3072
	s_add_u32 s2, s2, 0x1000
	s_addc_u32 s3, s3, 0
	global_load_dwordx4 v[50:53], v1, s[2:3]
	global_load_dwordx4 v[54:57], v1, s[2:3] offset:1024
	global_load_dwordx4 v[58:61], v1, s[2:3] offset:2048
	global_load_dwordx4 v[62:65], v1, s[2:3] offset:3072
	s_waitcnt vmcnt(8)
	s_add_u32 s2, s2, 0x1000
	s_addc_u32 s3, s3, 0
	global_load_dwordx4 v[2:5], v1, s[2:3]
	global_load_dwordx4 v[6:9], v1, s[2:3] offset:1024
	global_load_dwordx4 v[10:13], v1, s[2:3] offset:2048
	global_load_dwordx4 v[14:17], v1, s[2:3] offset:3072
	s_add_u32 s2, s2, 0x1000
	s_addc_u32 s3, s3, 0
	global_load_dwordx4 v[18:21], v1, s[2:3]
	global_load_dwordx4 v[22:25], v1, s[2:3] offset:1024
	global_load_dwordx4 v[26:29], v1, s[2:3] offset:2048
	global_load_dwordx4 v[30:33], v1, s[2:3] offset:3072
	s_add_u32 s2, s2, 0x1000
	s_addc_u32 s3, s3, 0
	global_load_dwordx4 v[34:37], v1, s[2:3]
	global_load_dwordx4 v[38:41], v1, s[2:3] offset:1024
	global_load_dwordx4 v[42:45], v1, s[2:3] offset:2048
	global_load_dwordx4 v[46:49], v1, s[2:3] offset:3072
	s_add_u32 s2, s2, 0x1000
	s_addc_u32 s3, s3, 0
	global_load_dwordx4 v[50:53], v1, s[2:3]
	global_load_dwordx4 v[54:57], v1, s[2:3] offset:1024
	global_load_dwordx4 v[58:61], v1, s[2:3] offset:2048
	global_load_dwordx4 v[62:65], v1, s[2:3] offset:3072
	s_waitcnt vmcnt(8)
	s_add_u32 s2, s2, 0x1000
	s_addc_u32 s3, s3, 0
	global_load_dwordx4 v[2:5], v1, s[2:3]
	global_load_dwordx4 v[6:9], v1, s[2:3] offset:1024
	global_load_dwordx4 v[10:13], v1, s[2:3] offset:2048
	global_load_dwordx4 v[14:17], v1, s[2:3] offset:3072
	s_add_u32 s2, s2, 0x1000
	s_addc_u32 s3, s3, 0
	global_load_dwordx4 v[18:21], v1, s[2:3]
	global_load_dwordx4 v[22:25], v1, s[2:3] offset:1024
	global_load_dwordx4 v[26:29], v1, s[2:3] offset:2048
	global_load_dwordx4 v[30:33], v1, s[2:3] offset:3072
	s_add_u32 s2, s2, 0x1000
	s_addc_u32 s3, s3, 0
	global_load_dwordx4 v[34:37], v1, s[2:3]
	global_load_dwordx4 v[38:41], v1, s[2:3] offset:1024
	global_load_dwordx4 v[42:45], v1, s[2:3] offset:2048
	global_load_dwordx4 v[46:49], v1, s[2:3] offset:3072
	s_add_u32 s2, s2, 0x1000
	s_addc_u32 s3, s3, 0
	global_load_dwordx4 v[50:53], v1, s[2:3]
	global_load_dwordx4 v[54:57], v1, s[2:3] offset:1024
	global_load_dwordx4 v[58:61], v1, s[2:3] offset:2048
	global_load_dwordx4 v[62:65], v1, s[2:3] offset:3072
	s_waitcnt vmcnt(0)
	s_ashr_i32 s33, s93, 31
	s_lshr_b32 s0, s33, 29
	s_add_i32 s6, s93, s0
	s_and_b32 s0, s6, -8
	s_sub_i32 s3, s93, s0
	s_cmp_gt_i32 s3, -1
	s_cbranch_scc0 .LBB0_725
	s_lshl_b32 s2, s3, 8
	s_ashr_i32 s0, s6, 3
	s_cbranch_execz .LBB0_726
	s_branch .LBB0_727
